# MLA item prologue: second K chunks requested with the first, tile 1 staged and tile 2 requested mid peeled iteration
# speedup vs baseline: 1.0027x; 1.0027x over previous
.LBB0_246:
	s_and_b64 vcc, exec, s[2:3]
	s_cbranch_vccz .LBB0_217
	s_ashr_i32 s2, s86, 4
	s_ashr_i32 s6, s86, 7
	s_and_b32 s8, s2, 7
	s_ashr_i32 s7, s6, 31
	s_mul_i32 s3, s6, 0xc00000
	v_readlane_b32 s4, v252, 54
	s_mul_hi_i32 s0, s6, 0xc00000
	v_readlane_b32 s5, v252, 55
	s_add_u32 s3, s4, s3
	s_addc_u32 s0, s5, s0
	s_mul_i32 s4, s8, 0xc0
	s_add_u32 s4, s3, s4
	s_addc_u32 s5, s0, 0
	s_ashr_i32 s3, s2, 31
	s_mul_i32 s9, s2, 0x180000
	v_readlane_b32 s10, v252, 56
	s_mul_hi_i32 s0, s2, 0x180000
	v_readlane_b32 s11, v252, 57
	s_add_u32 s10, s10, s9
	s_addc_u32 s11, s11, s0
	s_lshl_b64 s[2:3], s[2:3], 20
	v_readlane_b32 s12, v252, 58
	v_readlane_b32 s13, v252, 59
	s_add_u32 s2, s12, s2
	s_addc_u32 s3, s13, s3
	s_lshl_b64 s[12:13], s[6:7], 20
	v_readlane_b32 s14, v252, 50
	v_readlane_b32 s15, v252, 51
	s_add_u32 s12, s14, s12
	s_addc_u32 s13, s15, s13
	s_lshl_b32 s0, s86, 9
	v_mov_b32_e32 v88, v204
	s_and_b32 s0, s0, 0x1e00
	s_movk_i32 s9, 0xc0
	v_and_b32_e32 v0, 0xffffffc0, v88
	v_and_b32_e32 v109, 31, v88
	v_add_u32_e32 v0, s0, v0
	v_or_b32_e32 v192, v0, v109
	v_or_b32_e32 v190, 32, v192
	v_mov_b64_e32 v[0:1], s[4:5]
	s_movk_i32 s0, 0x600
	v_mad_i64_i32 v[2:3], s[4:5], v192, s0, v[0:1]
	v_mad_i64_i32 v[0:1], s[4:5], v190, s0, v[0:1]
	s_movk_i32 s0, 0x100
	v_cmp_gt_i32_e64 s[4:5], s0, v88
	s_mov_b32 s0, 0x2aaaaaab
	v_mul_hi_i32 v32, v88, s0
	v_lshrrev_b32_e32 v33, 31, v32
	v_ashrrev_i32_e32 v32, 1, v32
	v_add_u32_e32 v89, v32, v33
	v_mul_lo_u32 v84, v89, 12
	v_sub_u32_e32 v90, v88, v84
	v_mov_b64_e32 v[32:33], s[10:11]
	v_lshlrev_b32_e32 v84, 3, v90
	v_add_u32_e32 v86, 0x200, v88
	v_mad_i64_i32 v[34:35], s[10:11], v89, s9, v[32:33]
	v_ashrrev_i32_e32 v85, 31, v84
	v_bfe_u32 v215, v88, 5, 1
	v_lshl_add_u64 v[194:195], v[84:85], 1, v[34:35]
	v_cndmask_b32_e64 v34, v88, v86, s[4:5]
	v_lshlrev_b32_e32 v188, 4, v215
	v_mul_hi_i32 v35, v34, s0
	v_ashrrev_i32_e32 v193, 31, v192
	v_lshl_add_u64 v[2:3], v[2:3], 0, v[188:189]
	v_lshrrev_b32_e32 v84, 31, v35
	v_ashrrev_i32_e32 v35, 1, v35
	s_waitcnt lgkmcnt(0)
	global_load_dwordx4 v[80:83], v[2:3], off
	global_load_dwordx4 v[76:79], v[2:3], off offset:32
	global_load_dwordx4 v[72:75], v[2:3], off offset:64
	global_load_dwordx4 v[68:71], v[2:3], off offset:96
	global_load_dwordx4 v[56:59], v[2:3], off offset:128
	global_load_dwordx4 v[48:51], v[2:3], off offset:160
	v_lshlrev_b64 v[2:3], 7, v[192:193]
	v_add_u32_e32 v91, v35, v84
	v_lshl_add_u64 v[2:3], s[12:13], 0, v[2:3]
	v_lshlrev_b32_e32 v12, 5, v215
	v_mov_b32_e32 v13, v189
	v_mul_lo_u32 v35, v91, 12
	v_lshl_add_u64 v[2:3], v[2:3], 0, v[12:13]
	v_ashrrev_i32_e32 v191, 31, v190
	v_lshl_add_u64 v[0:1], v[0:1], 0, v[188:189]
	v_sub_u32_e32 v92, v34, v35
	global_load_dwordx4 v[44:47], v[2:3], off offset:16
	global_load_dwordx4 v[60:63], v[2:3], off
	global_load_dwordx4 v[52:55], v[2:3], off offset:80
	global_load_dwordx4 v[64:67], v[2:3], off offset:64
	global_load_dwordx4 v[40:43], v[0:1], off
	global_load_dwordx4 v[36:39], v[0:1], off offset:32
	global_load_dwordx4 v[28:31], v[0:1], off offset:64
	global_load_dwordx4 v[24:27], v[0:1], off offset:96
	global_load_dwordx4 v[8:11], v[0:1], off offset:128
	global_load_dwordx4 v[4:7], v[0:1], off offset:160
	v_lshlrev_b64 v[0:1], 7, v[190:191]
	v_lshlrev_b32_e32 v34, 3, v92
	v_ashrrev_i32_e32 v84, 3, v88
	v_lshl_add_u64 v[0:1], s[12:13], 0, v[0:1]
	v_mad_i64_i32 v[32:33], s[10:11], v91, s9, v[32:33]
	v_ashrrev_i32_e32 v35, 31, v34
	v_ashrrev_i32_e32 v85, 31, v84
	v_lshl_add_u64 v[20:21], v[0:1], 0, v[12:13]
	v_lshl_add_u64 v[196:197], v[34:35], 1, v[32:33]
	v_lshlrev_b64 v[32:33], 14, v[84:85]
	v_and_b32_e32 v34, 7, v88
	global_load_dwordx4 v[0:3], v[20:21], off offset:16
	global_load_dwordx4 v[16:19], v[20:21], off
	global_load_dwordx4 v[12:15], v[20:21], off offset:80
	s_nop 0
	global_load_dwordx4 v[20:23], v[20:21], off offset:64
	v_lshl_add_u64 v[32:33], s[2:3], 0, v[32:33]
	v_lshlrev_b32_e32 v86, 4, v34
	v_mov_b32_e32 v87, v189
	s_movk_i32 s0, 0xd0
	v_lshl_add_u64 v[198:199], v[32:33], 0, v[86:87]
	v_mul_lo_u32 v32, v89, s0
	v_lshl_add_u32 v216, v90, 4, v32
	v_mul_lo_u32 v32, v91, s0
	v_lshl_add_u32 v217, v92, 4, v32
	global_load_dwordx4 v[90:93], v[194:195], off
	global_load_dwordx4 v[32:35], v[198:199], off
	global_load_dwordx4 v[240:243], v[196:197], off
	s_movk_i32 s9, 0xd0
	v_add_u32_e32 v112, 0, v216
	v_add_u32_e32 v111, 0, v217
	s_waitcnt vmcnt(0)
	ds_write_b128 v112, v[90:93]
	s_and_saveexec_b64 s[2:3], s[4:5]
	ds_write_b128 v111, v[240:243]
.LBB0_249:
	s_or_b64 exec, exec, s[2:3]
	v_lshlrev_b32_e32 v90, 16, v80
	v_and_b32_e32 v91, 0xffff0000, v80
	s_mov_b32 s10, 0x3e16c740
	v_lshlrev_b32_e32 v80, 16, v81
	v_and_b32_e32 v81, 0xffff0000, v81
	v_pk_mul_f32 v[80:81], v[80:81], s[10:11] op_sel_hi:[1,0]
	s_movk_i32 s2, 0x90
	v_cvt_pk_bf16_f32 v129, v80, v81
	v_lshlrev_b32_e32 v80, 16, v82
	v_and_b32_e32 v81, 0xffff0000, v82
	v_pk_mul_f32 v[80:81], v[80:81], s[10:11] op_sel_hi:[1,0]
	s_movk_i32 s0, 0x3000
	v_cvt_pk_bf16_f32 v130, v80, v81
	v_lshlrev_b32_e32 v80, 16, v83
	v_and_b32_e32 v81, 0xffff0000, v83
	v_pk_mul_f32 v[80:81], v[80:81], s[10:11] op_sel_hi:[1,0]
	v_pk_mul_f32 v[90:91], v[90:91], s[10:11] op_sel_hi:[1,0]
	v_cvt_pk_bf16_f32 v131, v80, v81
	v_lshlrev_b32_e32 v80, 16, v76
	v_and_b32_e32 v81, 0xffff0000, v76
	v_lshlrev_b32_e32 v76, 16, v77
	v_and_b32_e32 v77, 0xffff0000, v77
	v_pk_mul_f32 v[76:77], v[76:77], s[10:11] op_sel_hi:[1,0]
	v_pk_mul_f32 v[80:81], v[80:81], s[10:11] op_sel_hi:[1,0]
	v_cvt_pk_bf16_f32 v133, v76, v77
	v_lshlrev_b32_e32 v76, 16, v78
	v_and_b32_e32 v77, 0xffff0000, v78
	v_pk_mul_f32 v[76:77], v[76:77], s[10:11] op_sel_hi:[1,0]
	v_cvt_pk_bf16_f32 v128, v90, v91
	v_cvt_pk_bf16_f32 v134, v76, v77
	v_lshlrev_b32_e32 v76, 16, v79
	v_and_b32_e32 v77, 0xffff0000, v79
	v_pk_mul_f32 v[76:77], v[76:77], s[10:11] op_sel_hi:[1,0]
	v_cvt_pk_bf16_f32 v132, v80, v81
	v_cvt_pk_bf16_f32 v135, v76, v77
	v_lshlrev_b32_e32 v76, 16, v72
	v_and_b32_e32 v77, 0xffff0000, v72
	v_lshlrev_b32_e32 v72, 16, v73
	v_and_b32_e32 v73, 0xffff0000, v73
	v_pk_mul_f32 v[72:73], v[72:73], s[10:11] op_sel_hi:[1,0]
	v_pk_mul_f32 v[76:77], v[76:77], s[10:11] op_sel_hi:[1,0]
	v_cvt_pk_bf16_f32 v137, v72, v73
	v_lshlrev_b32_e32 v72, 16, v74
	v_and_b32_e32 v73, 0xffff0000, v74
	v_pk_mul_f32 v[72:73], v[72:73], s[10:11] op_sel_hi:[1,0]
	v_cvt_pk_bf16_f32 v136, v76, v77
	v_cvt_pk_bf16_f32 v138, v72, v73
	v_lshlrev_b32_e32 v72, 16, v75
	v_and_b32_e32 v73, 0xffff0000, v75
	v_pk_mul_f32 v[72:73], v[72:73], s[10:11] op_sel_hi:[1,0]
	s_nop 0
	v_cvt_pk_bf16_f32 v139, v72, v73
	v_lshlrev_b32_e32 v72, 16, v68
	v_and_b32_e32 v73, 0xffff0000, v68
	v_lshlrev_b32_e32 v68, 16, v69
	v_and_b32_e32 v69, 0xffff0000, v69
	v_pk_mul_f32 v[68:69], v[68:69], s[10:11] op_sel_hi:[1,0]
	v_pk_mul_f32 v[72:73], v[72:73], s[10:11] op_sel_hi:[1,0]
	v_cvt_pk_bf16_f32 v141, v68, v69
	v_lshlrev_b32_e32 v68, 16, v70
	v_and_b32_e32 v69, 0xffff0000, v70
	v_pk_mul_f32 v[68:69], v[68:69], s[10:11] op_sel_hi:[1,0]
	v_lshlrev_b32_e32 v70, 16, v48
	v_cvt_pk_bf16_f32 v142, v68, v69
	v_lshlrev_b32_e32 v68, 16, v71
	v_and_b32_e32 v69, 0xffff0000, v71
	v_pk_mul_f32 v[68:69], v[68:69], s[10:11] op_sel_hi:[1,0]
	v_and_b32_e32 v71, 0xffff0000, v48
	v_cvt_pk_bf16_f32 v143, v68, v69
	v_lshlrev_b32_e32 v68, 16, v56
	v_and_b32_e32 v69, 0xffff0000, v56
	v_cvt_pk_bf16_f32 v140, v72, v73
	v_pk_mul_f32 v[72:73], v[64:65], v[70:71]
	v_pk_mul_f32 v[64:65], v[64:65], v[68:69]
	v_pk_fma_f32 v[72:73], v[60:61], v[68:69], v[72:73] neg_lo:[0,0,1] neg_hi:[0,0,1]
	v_pk_fma_f32 v[60:61], v[60:61], v[70:71], v[64:65]
	v_lshlrev_b32_e32 v48, 16, v49
	v_pk_mul_f32 v[60:61], v[60:61], s[10:11] op_sel_hi:[1,0]
	v_and_b32_e32 v49, 0xffff0000, v49
	v_cvt_pk_bf16_f32 v148, v60, v61
	v_lshlrev_b32_e32 v56, 16, v57
	v_and_b32_e32 v57, 0xffff0000, v57
	v_pk_mul_f32 v[60:61], v[66:67], v[48:49]
	v_pk_mul_f32 v[72:73], v[72:73], s[10:11] op_sel_hi:[1,0]
	v_pk_fma_f32 v[60:61], v[62:63], v[56:57], v[60:61] neg_lo:[0,0,1] neg_hi:[0,0,1]
	v_pk_mul_f32 v[56:57], v[66:67], v[56:57]
	v_pk_mul_f32 v[60:61], v[60:61], s[10:11] op_sel_hi:[1,0]
	v_pk_fma_f32 v[48:49], v[62:63], v[48:49], v[56:57]
	v_lshlrev_b32_e32 v56, 16, v50
	v_pk_mul_f32 v[48:49], v[48:49], s[10:11] op_sel_hi:[1,0]
	v_and_b32_e32 v57, 0xffff0000, v50
	v_cvt_pk_bf16_f32 v145, v60, v61
	v_cvt_pk_bf16_f32 v149, v48, v49
	v_lshlrev_b32_e32 v48, 16, v58
	v_and_b32_e32 v49, 0xffff0000, v58
	v_pk_mul_f32 v[60:61], v[52:53], v[56:57]
	v_cvt_pk_bf16_f32 v144, v72, v73
	v_pk_fma_f32 v[60:61], v[44:45], v[48:49], v[60:61] neg_lo:[0,0,1] neg_hi:[0,0,1]
	v_pk_mul_f32 v[48:49], v[52:53], v[48:49]
	v_pk_mul_f32 v[60:61], v[60:61], s[10:11] op_sel_hi:[1,0]
	v_pk_fma_f32 v[44:45], v[44:45], v[56:57], v[48:49]
	v_lshlrev_b32_e32 v48, 16, v51
	v_pk_mul_f32 v[44:45], v[44:45], s[10:11] op_sel_hi:[1,0]
	v_and_b32_e32 v49, 0xffff0000, v51
	v_cvt_pk_bf16_f32 v150, v44, v45
	v_lshlrev_b32_e32 v44, 16, v59
	v_and_b32_e32 v45, 0xffff0000, v59
	v_pk_mul_f32 v[50:51], v[54:55], v[48:49]
	v_cvt_pk_bf16_f32 v146, v60, v61
	v_pk_fma_f32 v[50:51], v[46:47], v[44:45], v[50:51] neg_lo:[0,0,1] neg_hi:[0,0,1]
	v_pk_mul_f32 v[44:45], v[54:55], v[44:45]
	v_pk_mul_f32 v[50:51], v[50:51], s[10:11] op_sel_hi:[1,0]
	v_pk_fma_f32 v[44:45], v[46:47], v[48:49], v[44:45]
	v_cvt_pk_bf16_f32 v147, v50, v51
	v_pk_mul_f32 v[44:45], v[44:45], s[10:11] op_sel_hi:[1,0]
	s_nop 0
	v_cvt_pk_bf16_f32 v151, v44, v45
	v_lshlrev_b32_e32 v44, 16, v40
	v_and_b32_e32 v45, 0xffff0000, v40
	v_lshlrev_b32_e32 v40, 16, v41
	v_and_b32_e32 v41, 0xffff0000, v41
	v_pk_mul_f32 v[40:41], v[40:41], s[10:11] op_sel_hi:[1,0]
	v_pk_mul_f32 v[44:45], v[44:45], s[10:11] op_sel_hi:[1,0]
	v_cvt_pk_bf16_f32 v153, v40, v41
	v_lshlrev_b32_e32 v40, 16, v42
	v_and_b32_e32 v41, 0xffff0000, v42
	v_pk_mul_f32 v[40:41], v[40:41], s[10:11] op_sel_hi:[1,0]
	v_cvt_pk_bf16_f32 v152, v44, v45
	v_cvt_pk_bf16_f32 v154, v40, v41
	v_lshlrev_b32_e32 v40, 16, v43
	v_and_b32_e32 v41, 0xffff0000, v43
	v_pk_mul_f32 v[40:41], v[40:41], s[10:11] op_sel_hi:[1,0]
	s_nop 0
	v_cvt_pk_bf16_f32 v155, v40, v41
	v_lshlrev_b32_e32 v40, 16, v36
	v_and_b32_e32 v41, 0xffff0000, v36
	v_lshlrev_b32_e32 v36, 16, v37
	v_and_b32_e32 v37, 0xffff0000, v37
	v_pk_mul_f32 v[36:37], v[36:37], s[10:11] op_sel_hi:[1,0]
	v_pk_mul_f32 v[40:41], v[40:41], s[10:11] op_sel_hi:[1,0]
	v_cvt_pk_bf16_f32 v157, v36, v37
	v_lshlrev_b32_e32 v36, 16, v38
	v_and_b32_e32 v37, 0xffff0000, v38
	v_pk_mul_f32 v[36:37], v[36:37], s[10:11] op_sel_hi:[1,0]
	v_lshlrev_b32_e32 v38, 3, v88
	v_cvt_pk_bf16_f32 v158, v36, v37
	v_lshlrev_b32_e32 v36, 16, v39
	v_and_b32_e32 v37, 0xffff0000, v39
	v_pk_mul_f32 v[36:37], v[36:37], s[10:11] op_sel_hi:[1,0]
	v_cvt_pk_bf16_f32 v156, v40, v41
	v_cvt_pk_bf16_f32 v159, v36, v37
	v_lshlrev_b32_e32 v36, 16, v28
	v_and_b32_e32 v37, 0xffff0000, v28
	v_pk_mul_f32 v[36:37], v[36:37], s[10:11] op_sel_hi:[1,0]
	v_lshlrev_b32_e32 v28, 16, v29
	v_cvt_pk_bf16_f32 v160, v36, v37
	v_mul_lo_u32 v36, v84, s2
	v_and_b32_e32 v37, 0x60, v86
	v_and_or_b32 v36, v38, 8, v36
	v_add_u32_e32 v219, v36, v37
	v_add_u32_e32 v113, 0, v219
	v_add_u32_e32 v36, 0x3000, v113
	ds_write2_b64 v36, v[32:33], v[34:35] offset0:128 offset1:130
	v_add_co_u32_e32 v32, vcc, s0, v194
	s_waitcnt lgkmcnt(0)
	s_nop 0
	v_addc_co_u32_e32 v33, vcc, 0, v195, vcc
	s_barrier
	global_load_dwordx4 v[100:103], v[32:33], off
	global_load_dwordx4 v[96:99], v[198:199], off offset:128
	s_movk_i32 vcc_lo, 0x3000
	s_mov_b32 vcc_hi, 0
	v_lshl_add_u64 v[244:245], v[196:197], 0, vcc
	global_load_dwordx4 v[244:247], v[244:245], off
	v_and_b32_e32 v29, 0xffff0000, v29
	v_pk_mul_f32 v[28:29], v[28:29], s[10:11] op_sel_hi:[1,0]
	s_nop 0
	v_cvt_pk_bf16_f32 v161, v28, v29
	v_lshlrev_b32_e32 v28, 16, v30
	v_and_b32_e32 v29, 0xffff0000, v30
	v_pk_mul_f32 v[28:29], v[28:29], s[10:11] op_sel_hi:[1,0]
	s_nop 0
	v_cvt_pk_bf16_f32 v162, v28, v29
	v_lshlrev_b32_e32 v28, 16, v31
	v_and_b32_e32 v29, 0xffff0000, v31
	v_pk_mul_f32 v[28:29], v[28:29], s[10:11] op_sel_hi:[1,0]
	s_nop 0
	v_cvt_pk_bf16_f32 v163, v28, v29
	v_lshlrev_b32_e32 v28, 16, v24
	v_and_b32_e32 v29, 0xffff0000, v24
	v_lshlrev_b32_e32 v24, 16, v25
	v_and_b32_e32 v25, 0xffff0000, v25
	v_pk_mul_f32 v[24:25], v[24:25], s[10:11] op_sel_hi:[1,0]
	v_pk_mul_f32 v[28:29], v[28:29], s[10:11] op_sel_hi:[1,0]
	v_cvt_pk_bf16_f32 v165, v24, v25
	v_lshlrev_b32_e32 v24, 16, v26
	v_and_b32_e32 v25, 0xffff0000, v26
	v_pk_mul_f32 v[24:25], v[24:25], s[10:11] op_sel_hi:[1,0]
	v_lshlrev_b32_e32 v26, 16, v4
	v_cvt_pk_bf16_f32 v166, v24, v25
	v_lshlrev_b32_e32 v24, 16, v27
	v_and_b32_e32 v25, 0xffff0000, v27
	v_pk_mul_f32 v[24:25], v[24:25], s[10:11] op_sel_hi:[1,0]
	v_and_b32_e32 v27, 0xffff0000, v4
	v_cvt_pk_bf16_f32 v167, v24, v25
	v_lshlrev_b32_e32 v24, 16, v8
	v_and_b32_e32 v25, 0xffff0000, v8
	v_cvt_pk_bf16_f32 v164, v28, v29
	v_pk_mul_f32 v[28:29], v[20:21], v[26:27]
	v_pk_mul_f32 v[20:21], v[20:21], v[24:25]
	v_pk_fma_f32 v[28:29], v[16:17], v[24:25], v[28:29] neg_lo:[0,0,1] neg_hi:[0,0,1]
	v_pk_fma_f32 v[16:17], v[16:17], v[26:27], v[20:21]
	v_lshlrev_b32_e32 v4, 16, v5
	v_pk_mul_f32 v[16:17], v[16:17], s[10:11] op_sel_hi:[1,0]
	v_and_b32_e32 v5, 0xffff0000, v5
	v_cvt_pk_bf16_f32 v172, v16, v17
	v_lshlrev_b32_e32 v8, 16, v9
	v_and_b32_e32 v9, 0xffff0000, v9
	v_pk_mul_f32 v[16:17], v[22:23], v[4:5]
	v_pk_mul_f32 v[28:29], v[28:29], s[10:11] op_sel_hi:[1,0]
	v_pk_fma_f32 v[16:17], v[18:19], v[8:9], v[16:17] neg_lo:[0,0,1] neg_hi:[0,0,1]
	v_pk_mul_f32 v[8:9], v[22:23], v[8:9]
	v_pk_mul_f32 v[16:17], v[16:17], s[10:11] op_sel_hi:[1,0]
	v_pk_fma_f32 v[4:5], v[18:19], v[4:5], v[8:9]
	v_lshlrev_b32_e32 v8, 16, v6
	v_pk_mul_f32 v[4:5], v[4:5], s[10:11] op_sel_hi:[1,0]
	v_and_b32_e32 v9, 0xffff0000, v6
	v_cvt_pk_bf16_f32 v169, v16, v17
	v_cvt_pk_bf16_f32 v173, v4, v5
	v_lshlrev_b32_e32 v4, 16, v10
	v_and_b32_e32 v5, 0xffff0000, v10
	v_pk_mul_f32 v[16:17], v[12:13], v[8:9]
	v_cvt_pk_bf16_f32 v168, v28, v29
	v_pk_fma_f32 v[16:17], v[0:1], v[4:5], v[16:17] neg_lo:[0,0,1] neg_hi:[0,0,1]
	v_pk_mul_f32 v[4:5], v[12:13], v[4:5]
	v_pk_mul_f32 v[16:17], v[16:17], s[10:11] op_sel_hi:[1,0]
	v_pk_fma_f32 v[0:1], v[0:1], v[8:9], v[4:5]
	v_lshlrev_b32_e32 v4, 16, v7
	v_pk_mul_f32 v[0:1], v[0:1], s[10:11] op_sel_hi:[1,0]
	v_and_b32_e32 v5, 0xffff0000, v7
	v_cvt_pk_bf16_f32 v174, v0, v1
	v_lshlrev_b32_e32 v0, 16, v11
	v_and_b32_e32 v1, 0xffff0000, v11
	v_pk_mul_f32 v[6:7], v[14:15], v[4:5]
	v_cvt_pk_bf16_f32 v170, v16, v17
	v_pk_fma_f32 v[6:7], v[2:3], v[0:1], v[6:7] neg_lo:[0,0,1] neg_hi:[0,0,1]
	v_pk_mul_f32 v[0:1], v[14:15], v[0:1]
	v_pk_mul_f32 v[6:7], v[6:7], s[10:11] op_sel_hi:[1,0]
	v_pk_fma_f32 v[0:1], v[2:3], v[4:5], v[0:1]
	v_cvt_pk_bf16_f32 v171, v6, v7
	v_pk_mul_f32 v[0:1], v[0:1], s[10:11] op_sel_hi:[1,0]
	s_nop 0
	v_cvt_pk_bf16_f32 v175, v0, v1
	v_and_b32_e32 v1, 64, v207
	v_xor_b32_e32 v0, 32, v207
	v_add_u32_e32 v1, 64, v1
	v_cmp_lt_i32_e32 vcc, v0, v1
	s_nop 1
	v_cndmask_b32_e32 v0, v207, v0, vcc
	v_lshlrev_b32_e32 v218, 2, v0
	v_add_u32_e32 v220, 0, v188
	v_mad_u32_u24 v80, v109, s9, v220
	ds_read_b128 v[32:35], v80
	ds_read_b128 v[40:43], v80 offset:32
	v_readlane_b32 s12, v254, 57
	v_readlane_b32 s13, v254, 58
	v_readlane_b32 s14, v254, 59
	v_readlane_b32 s15, v254, 60
	v_readlane_b32 s26, v255, 7
	v_readlane_b32 s27, v255, 8
	v_readlane_b32 s16, v254, 61
	v_readlane_b32 s17, v254, 62
	v_readlane_b32 s18, v254, 63
	v_readlane_b32 s19, v255, 0
	v_readlane_b32 s20, v255, 1
	v_readlane_b32 s21, v255, 2
	v_readlane_b32 s22, v255, 3
	v_readlane_b32 s23, v255, 4
	v_readlane_b32 s24, v255, 5
	v_readlane_b32 s25, v255, 6
	s_mov_b32 s13, s12
	s_mov_b32 s14, s12
	s_mov_b32 s15, s12
	s_mov_b32 s26, s12
	s_mov_b32 s27, s12
	s_mov_b32 s0, s12
	s_mov_b32 s16, s12
	s_mov_b32 s17, s12
	s_mov_b32 s18, s12
	s_mov_b32 s19, s12
	s_mov_b32 s20, s12
	s_mov_b32 s21, s12
	s_mov_b32 s22, s12
	s_mov_b32 s23, s12
	s_mov_b32 s24, s12
	s_mov_b32 s25, s12
	v_writelane_b32 v254, s0, 57
	v_mov_b64_e32 v[78:79], s[26:27]
	v_mov_b64_e32 v[76:77], s[24:25]
	v_mov_b64_e32 v[74:75], s[22:23]
	v_mov_b64_e32 v[72:73], s[20:21]
	v_mov_b64_e32 v[70:71], s[18:19]
	v_mov_b64_e32 v[68:69], s[16:17]
	v_mov_b64_e32 v[66:67], s[14:15]
	v_mov_b64_e32 v[64:65], s[12:13]
	ds_read_b128 v[36:39], v80 offset:6656
	ds_read_b128 v[44:47], v80 offset:6688
	s_waitcnt lgkmcnt(3)
	v_mfma_f32_32x32x16_bf16 v[0:15], v[32:35], v[128:131], v[64:79]
	ds_read_b128 v[48:51], v80 offset:64
	ds_read_b128 v[56:59], v80 offset:96
	ds_read_b128 v[52:55], v80 offset:6720
	ds_read_b128 v[60:63], v80 offset:6752
	ds_read_b128 v[104:107], v80 offset:128
	ds_read_b128 v[184:187], v80 offset:160
	ds_read_b128 v[180:183], v80 offset:6784
	ds_read_b128 v[200:203], v80 offset:6816
	s_waitcnt lgkmcnt(9)
	v_mfma_f32_32x32x16_bf16 v[16:31], v[36:39], v[128:131], v[64:79]
	v_writelane_b32 v255, s7, 0
	v_writelane_b32 v255, s8, 1
	v_writelane_b32 v255, s9, 2
	v_writelane_b32 v254, s1, 58
	v_writelane_b32 v255, s10, 3
	v_mfma_f32_32x32x16_bf16 v[0:15], v[40:43], v[132:135], v[0:15]
	v_writelane_b32 v254, s2, 59
	v_writelane_b32 v255, s11, 4
	v_writelane_b32 v254, s3, 60
	v_writelane_b32 v255, s12, 5
	v_writelane_b32 v254, s4, 61
	v_writelane_b32 v255, s13, 6
	v_writelane_b32 v254, s5, 62
	s_waitcnt lgkmcnt(8)
	v_mfma_f32_32x32x16_bf16 v[16:31], v[44:47], v[132:135], v[16:31]
	v_writelane_b32 v255, s14, 7
	v_writelane_b32 v254, s6, 63
	v_writelane_b32 v255, s15, 8
	s_waitcnt lgkmcnt(7)
	v_mfma_f32_32x32x16_bf16 v[0:15], v[48:51], v[136:139], v[0:15]
	s_waitcnt lgkmcnt(5)
	v_mfma_f32_32x32x16_bf16 v[16:31], v[52:55], v[136:139], v[16:31]
	v_mfma_f32_32x32x16_bf16 v[0:15], v[56:59], v[140:143], v[0:15]
	s_waitcnt lgkmcnt(4)
	v_mfma_f32_32x32x16_bf16 v[16:31], v[60:63], v[140:143], v[16:31]
	s_waitcnt lgkmcnt(3)
	v_mfma_f32_32x32x16_bf16 v[0:15], v[104:107], v[144:147], v[0:15]
	s_waitcnt lgkmcnt(1)
	v_mfma_f32_32x32x16_bf16 v[16:31], v[180:183], v[144:147], v[16:31]
	v_mfma_f32_32x32x16_bf16 v[0:15], v[184:187], v[148:151], v[0:15]
	s_waitcnt lgkmcnt(0)
	v_mfma_f32_32x32x16_bf16 v[16:31], v[200:203], v[148:151], v[16:31]
	s_nop 9
	v_max3_f32 v80, v0, s43, v1
	v_max3_f32 v80, v80, v2, v3
	v_max3_f32 v80, v80, v4, v5
	v_max3_f32 v80, v80, v6, v7
	v_max3_f32 v80, v80, v8, v9
	v_max3_f32 v80, v80, v10, v11
	v_max3_f32 v80, v80, v12, v13
	v_max3_f32 v80, v80, v14, v15
	v_max3_f32 v108, v80, v16, v17
	v_mfma_f32_32x32x16_bf16 v[80:95], v[32:35], v[152:155], v[64:79]
	v_max3_f32 v32, v108, v18, v19
	v_max3_f32 v32, v32, v20, v21
	v_max3_f32 v32, v32, v22, v23
	v_max3_f32 v32, v32, v24, v25
	v_max3_f32 v32, v32, v26, v27
	v_max3_f32 v32, v32, v28, v29
	v_max3_f32 v32, v32, v30, v31
	v_mfma_f32_32x32x16_bf16 v[64:79], v[36:39], v[152:155], v[64:79]
	ds_bpermute_b32 v33, v218, v32
	s_waitcnt lgkmcnt(0)
	v_max_f32_e32 v33, v33, v33
	v_max_f32_e32 v108, v32, v33
	v_mfma_f32_32x32x16_bf16 v[80:95], v[40:43], v[156:159], v[80:95]
	v_sub_f32_e32 v0, v0, v108
	v_exp_f32_e32 v114, v0
	v_sub_f32_e32 v1, v1, v108
	v_exp_f32_e32 v115, v1
	v_sub_f32_e32 v2, v2, v108
	v_sub_f32_e32 v3, v3, v108
	v_sub_f32_e32 v227, v24, v108
	v_mfma_f32_32x32x16_bf16 v[64:79], v[44:47], v[156:159], v[64:79]
	v_sub_f32_e32 v228, v25, v108
	v_sub_f32_e32 v229, v26, v108
	v_sub_f32_e32 v232, v27, v108
	v_exp_f32_e32 v116, v2
	v_exp_f32_e32 v117, v3
	v_sub_f32_e32 v4, v4, v108
	v_sub_f32_e32 v5, v5, v108
	v_mfma_f32_32x32x16_bf16 v[80:95], v[48:51], v[160:163], v[80:95]
	v_sub_f32_e32 v6, v6, v108
	v_sub_f32_e32 v7, v7, v108
	v_sub_f32_e32 v8, v8, v108
	v_sub_f32_e32 v9, v9, v108
	v_sub_f32_e32 v10, v10, v108
	v_sub_f32_e32 v11, v11, v108
	v_exp_f32_e32 v118, v4
	v_mfma_f32_32x32x16_bf16 v[64:79], v[52:55], v[160:163], v[64:79]
	v_exp_f32_e32 v119, v5
	v_exp_f32_e32 v120, v6
	v_exp_f32_e32 v121, v7
	v_exp_f32_e32 v122, v8
	v_exp_f32_e32 v123, v9
	v_exp_f32_e32 v124, v10
	v_exp_f32_e32 v125, v11
	v_mfma_f32_32x32x16_bf16 v[80:95], v[56:59], v[164:167], v[80:95]
	v_sub_f32_e32 v20, v20, v108
	v_sub_f32_e32 v224, v21, v108
	v_sub_f32_e32 v225, v22, v108
	v_sub_f32_e32 v226, v23, v108
	v_sub_f32_e32 v32, v16, v108
	v_sub_f32_e32 v33, v17, v108
	v_sub_f32_e32 v34, v18, v108
	v_mfma_f32_32x32x16_bf16 v[64:79], v[60:63], v[164:167], v[64:79]
	v_sub_f32_e32 v35, v19, v108
	v_sub_f32_e32 v12, v12, v108
	v_sub_f32_e32 v13, v13, v108
	v_sub_f32_e32 v14, v14, v108
	v_sub_f32_e32 v15, v15, v108
	v_cvt_pk_bf16_f32 v16, v114, v115
	v_cvt_pk_bf16_f32 v17, v116, v117
	v_mfma_f32_32x32x16_bf16 v[80:95], v[104:107], v[168:171], v[80:95]
	v_cvt_pk_bf16_f32 v18, v118, v119
	v_cvt_pk_bf16_f32 v19, v120, v121
	v_sub_f32_e32 v233, v28, v108
	v_sub_f32_e32 v236, v29, v108
	v_sub_f32_e32 v237, v30, v108
	v_sub_f32_e32 v238, v31, v108
	v_exp_f32_e32 v126, v12
	v_mfma_f32_32x32x16_bf16 v[80:95], v[184:187], v[172:175], v[80:95]
	v_exp_f32_e32 v184, v225
	v_exp_f32_e32 v185, v226
	v_exp_f32_e32 v186, v227
	v_exp_f32_e32 v127, v13
	v_exp_f32_e32 v176, v14
	v_exp_f32_e32 v177, v15
	v_exp_f32_e32 v178, v32
	v_mfma_f32_32x32x16_bf16 v[64:79], v[180:183], v[168:171], v[64:79]
	s_nop 3
	v_max3_f32 v0, v80, s43, v81
	v_max3_f32 v0, v0, v82, v83
	v_max3_f32 v0, v0, v84, v85
	v_max3_f32 v0, v0, v86, v87
	v_max3_f32 v0, v0, v88, v89
	v_max3_f32 v0, v0, v90, v91
	v_max3_f32 v0, v0, v92, v93
	v_mfma_f32_32x32x16_bf16 v[64:79], v[200:203], v[172:175], v[64:79]
	v_max3_f32 v0, v0, v94, v95
	s_waitcnt vmcnt(0)
	ds_write_b128 v112, v[100:103] offset:22528
	s_mov_b64 vcc, exec
	s_and_b64 exec, exec, s[4:5]
	ds_write_b128 v111, v[244:247] offset:22528
	s_mov_b64 exec, vcc
	v_add_u32_e32 v240, 0x8800, v113
	ds_write2_b64 v240, v[96:97], v[98:99] offset0:128 offset1:130
	s_mov_b32 vcc_lo, 0x6000
	s_mov_b32 vcc_hi, 0
	v_lshl_add_u64 v[240:241], v[194:195], 0, vcc
	v_lshl_add_u64 v[244:245], v[196:197], 0, vcc
	s_movk_i32 vcc_lo, 0x100
	v_lshl_add_u64 v[248:249], v[198:199], 0, vcc
	global_load_dwordx4 v[240:243], v[240:241], off
	global_load_dwordx4 v[244:247], v[244:245], off
	global_load_dwordx4 v[248:251], v[248:249], off
	v_mad_u32_u24 v203, v109, s2, v220
	ds_read_b128 v[24:27], v203 offset:17920
	v_exp_f32_e32 v182, v20
	ds_read_b128 v[220:223], v203 offset:13344
	v_exp_f32_e32 v183, v224
	ds_read_b128 v[224:227], v203 offset:17952
	s_nop 4
	v_max3_f32 v0, v0, v64, v65
	v_max3_f32 v0, v0, v66, v67
	v_max3_f32 v0, v0, v68, v69
	v_max3_f32 v0, v0, v70, v71
	v_max3_f32 v0, v0, v72, v73
	v_max3_f32 v0, v0, v74, v75
	v_max3_f32 v0, v0, v76, v77
	v_max3_f32 v0, v0, v78, v79
	ds_bpermute_b32 v1, v218, v0
	v_exp_f32_e32 v179, v33
	v_exp_f32_e32 v180, v34
	v_exp_f32_e32 v181, v35
	s_waitcnt lgkmcnt(3)
	v_mfma_f32_32x32x16_bf16 v[48:63], v[24:27], v[16:19], 0
	s_waitcnt lgkmcnt(0)
	v_max_f32_e32 v1, v1, v1
	v_max_f32_e32 v110, v0, v1
	ds_read_b128 v[0:3], v203 offset:13312
	v_sub_f32_e32 v4, v80, v110
	v_sub_f32_e32 v5, v81, v110
	v_sub_f32_e32 v6, v82, v110
	v_sub_f32_e32 v7, v83, v110
	v_sub_f32_e32 v8, v84, v110
	v_sub_f32_e32 v9, v85, v110
	v_sub_f32_e32 v10, v86, v110
	v_sub_f32_e32 v11, v87, v110
	v_exp_f32_e32 v80, v4
	v_exp_f32_e32 v81, v5
	v_exp_f32_e32 v82, v6
	v_exp_f32_e32 v83, v7
	v_exp_f32_e32 v84, v8
	v_exp_f32_e32 v85, v9
	v_exp_f32_e32 v86, v10
	v_exp_f32_e32 v87, v11
	v_cvt_pk_bf16_f32 v20, v80, v81
	v_cvt_pk_bf16_f32 v21, v82, v83
	v_cvt_pk_bf16_f32 v22, v84, v85
	v_cvt_pk_bf16_f32 v23, v86, v87
	s_waitcnt lgkmcnt(0)
	v_mfma_f32_32x32x16_bf16 v[32:47], v[0:3], v[16:19], 0
	v_sub_f32_e32 v88, v88, v110
	v_sub_f32_e32 v89, v89, v110
	v_sub_f32_e32 v90, v90, v110
	v_sub_f32_e32 v91, v91, v110
	v_sub_f32_e32 v92, v92, v110
	v_sub_f32_e32 v93, v93, v110
	v_sub_f32_e32 v94, v94, v110
	v_mfma_f32_32x32x16_bf16 v[0:15], v[0:3], v[20:23], 0
	v_sub_f32_e32 v95, v95, v110
	v_exp_f32_e32 v88, v88
	v_exp_f32_e32 v89, v89
	v_exp_f32_e32 v90, v90
	v_exp_f32_e32 v91, v91
	v_exp_f32_e32 v92, v92
	v_exp_f32_e32 v93, v93
	v_mfma_f32_32x32x16_bf16 v[16:31], v[24:27], v[20:23], 0
	v_exp_f32_e32 v94, v94
	v_exp_f32_e32 v95, v95
	v_cvt_pk_bf16_f32 v104, v122, v123
	v_cvt_pk_bf16_f32 v105, v124, v125
	v_cvt_pk_bf16_f32 v106, v126, v127
	v_cvt_pk_bf16_f32 v107, v176, v177
	v_exp_f32_e32 v187, v228
	v_exp_f32_e32 v200, v229
	v_cvt_pk_bf16_f32 v228, v88, v89
	v_cvt_pk_bf16_f32 v229, v90, v91
	v_cvt_pk_bf16_f32 v230, v92, v93
	v_cvt_pk_bf16_f32 v231, v94, v95
	v_mfma_f32_32x32x16_bf16 v[32:47], v[220:223], v[104:107], v[32:47]
	v_sub_f32_e32 v64, v64, v110
	v_sub_f32_e32 v65, v65, v110
	v_sub_f32_e32 v66, v66, v110
	v_sub_f32_e32 v67, v67, v110
	v_sub_f32_e32 v68, v68, v110
	v_sub_f32_e32 v69, v69, v110
	v_sub_f32_e32 v70, v70, v110
	v_mfma_f32_32x32x16_bf16 v[0:15], v[220:223], v[228:231], v[0:15]
	v_sub_f32_e32 v71, v71, v110
	v_exp_f32_e32 v64, v64
	v_exp_f32_e32 v65, v65
	v_exp_f32_e32 v66, v66
	v_exp_f32_e32 v67, v67
	v_exp_f32_e32 v68, v68
	v_exp_f32_e32 v69, v69
	v_mfma_f32_32x32x16_bf16 v[48:63], v[224:227], v[104:107], v[48:63]
	ds_read_b128 v[104:107], v203 offset:13376
	v_exp_f32_e32 v70, v70
	v_exp_f32_e32 v71, v71
	v_exp_f32_e32 v201, v232
	v_exp_f32_e32 v202, v233
	v_cvt_pk_bf16_f32 v220, v178, v179
	v_cvt_pk_bf16_f32 v221, v180, v181
	v_mfma_f32_32x32x16_bf16 v[16:31], v[224:227], v[228:231], v[16:31]
	ds_read_b128 v[228:231], v203 offset:17984
	v_cvt_pk_bf16_f32 v224, v64, v65
	v_cvt_pk_bf16_f32 v225, v66, v67
	v_cvt_pk_bf16_f32 v226, v68, v69
	v_cvt_pk_bf16_f32 v227, v70, v71
	v_cvt_pk_bf16_f32 v222, v182, v183
	v_cvt_pk_bf16_f32 v223, v184, v185
	ds_read_b128 v[232:235], v203 offset:13408
	s_waitcnt lgkmcnt(2)
	v_mfma_f32_32x32x16_bf16 v[0:15], v[104:107], v[224:227], v[0:15]
	v_sub_f32_e32 v72, v72, v110
	v_sub_f32_e32 v73, v73, v110
	v_sub_f32_e32 v74, v74, v110
	v_sub_f32_e32 v75, v75, v110
	v_sub_f32_e32 v76, v76, v110
	v_sub_f32_e32 v77, v77, v110
	v_sub_f32_e32 v78, v78, v110
	s_waitcnt lgkmcnt(1)
	v_mfma_f32_32x32x16_bf16 v[16:31], v[228:231], v[224:227], v[16:31]
	ds_read_b128 v[224:227], v203 offset:18016
	v_sub_f32_e32 v79, v79, v110
	v_exp_f32_e32 v72, v72
	v_exp_f32_e32 v73, v73
	v_exp_f32_e32 v74, v74
	v_exp_f32_e32 v75, v75
	v_exp_f32_e32 v76, v76
	v_mfma_f32_32x32x16_bf16 v[32:47], v[104:107], v[220:223], v[32:47]
	v_exp_f32_e32 v104, v236
	v_exp_f32_e32 v105, v237
	v_exp_f32_e32 v106, v238
	v_exp_f32_e32 v77, v77
	v_exp_f32_e32 v78, v78
	v_exp_f32_e32 v79, v79
	v_cvt_pk_bf16_f32 v236, v186, v187
	v_mfma_f32_32x32x16_bf16 v[48:63], v[228:231], v[220:223], v[48:63]
	v_cvt_pk_bf16_f32 v237, v200, v201
	v_cvt_pk_bf16_f32 v238, v202, v104
	v_cvt_pk_bf16_f32 v239, v105, v106
	v_cvt_pk_bf16_f32 v220, v72, v73
	v_cvt_pk_bf16_f32 v221, v74, v75
	v_cvt_pk_bf16_f32 v222, v76, v77
	v_cvt_pk_bf16_f32 v223, v78, v79
	s_waitcnt lgkmcnt(1)
	v_mfma_f32_32x32x16_bf16 v[32:47], v[232:235], v[236:239], v[32:47]
	v_mfma_f32_32x32x16_bf16 v[0:15], v[232:235], v[220:223], v[0:15]
	s_waitcnt lgkmcnt(0)
	v_mfma_f32_32x32x16_bf16 v[48:63], v[224:227], v[236:239], v[48:63]
	v_mfma_f32_32x32x16_bf16 v[16:31], v[224:227], v[220:223], v[16:31]
	v_add_f32_e32 v100, 0, v114
	v_add_f32_e32 v80, 0, v80
	v_add_f32_e32 v100, v115, v100
	v_add_f32_e32 v80, v81, v80
	v_add_f32_e32 v100, v116, v100
	v_add_f32_e32 v80, v82, v80
	v_add_f32_e32 v100, v117, v100
	v_add_f32_e32 v80, v83, v80
	v_add_f32_e32 v100, v118, v100
	v_add_f32_e32 v80, v84, v80
	v_add_f32_e32 v100, v119, v100
	v_add_f32_e32 v80, v85, v80
	v_add_f32_e32 v100, v120, v100
	v_add_f32_e32 v80, v86, v80
	v_add_f32_e32 v100, v121, v100
	v_add_f32_e32 v80, v87, v80
	v_add_f32_e32 v100, v122, v100
	v_add_f32_e32 v80, v88, v80
	v_add_f32_e32 v100, v123, v100
	v_add_f32_e32 v80, v89, v80
	v_add_f32_e32 v100, v124, v100
	v_add_f32_e32 v80, v90, v80
	v_add_f32_e32 v100, v125, v100
	v_add_f32_e32 v80, v91, v80
	v_add_f32_e32 v100, v126, v100
	v_add_f32_e32 v80, v92, v80
	v_add_f32_e32 v100, v127, v100
	v_add_f32_e32 v80, v93, v80
	v_add_f32_e32 v100, v176, v100
	v_add_f32_e32 v80, v94, v80
	v_add_f32_e32 v100, v177, v100
	v_add_f32_e32 v80, v95, v80
	v_add_f32_e32 v100, v178, v100
	v_add_f32_e32 v64, v64, v80
	v_add_f32_e32 v100, v179, v100
	v_add_f32_e32 v64, v65, v64
	v_add_f32_e32 v100, v180, v100
	v_add_f32_e32 v64, v66, v64
	v_add_f32_e32 v100, v181, v100
	v_add_f32_e32 v64, v67, v64
	v_add_f32_e32 v100, v182, v100
	v_add_f32_e32 v64, v68, v64
	v_add_f32_e32 v100, v183, v100
	v_add_f32_e32 v64, v69, v64
	v_add_f32_e32 v100, v184, v100
	v_add_f32_e32 v64, v70, v64
	v_add_f32_e32 v100, v185, v100
	v_add_f32_e32 v64, v71, v64
	v_add_f32_e32 v100, v186, v100
	v_add_f32_e32 v64, v72, v64
	v_add_f32_e32 v100, v187, v100
	v_add_f32_e32 v64, v73, v64
	v_add_f32_e32 v100, v200, v100
	v_add_f32_e32 v64, v74, v64
	v_add_f32_e32 v100, v201, v100
	v_add_f32_e32 v64, v75, v64
	v_add_f32_e32 v100, v202, v100
	v_add_f32_e32 v64, v76, v64
	v_add_f32_e32 v100, v104, v100
	v_add_f32_e32 v64, v77, v64
	v_add_f32_e32 v100, v105, v100
	v_add_f32_e32 v64, v78, v64
	v_mul_u32_u24_e32 v220, 0xd0, v109
	v_mul_u32_u24_e32 v221, 0x90, v109
	v_add_f32_e32 v109, v106, v100
	v_add_f32_e32 v111, v79, v64
	v_pk_add_f32 v[202:203], v[108:109], 0 op_sel_hi:[1,0]
	v_pk_add_f32 v[200:201], v[110:111], 0 op_sel_hi:[1,0]
	s_mov_b32 s9, 2
	s_mov_b32 s3, 0
	s_mov_b32 s2, 0x6000
	s_movk_i32 s0, 0x100
	s_movk_i32 s2, 0x5800
	v_add3_u32 v220, v220, v188, s2
	s_movk_i32 s2, 0x3400
	v_add3_u32 v221, v221, v188, s2
	v_add_u32_e32 v238, 0xe000, v219
	v_add_u32_e32 v219, 0x3000, v219
	v_xor_b32_e32 v64, 0x80000000, v202
	v_mov_b32_e32 v65, v64
	v_mov_b32_e32 v66, v64
	v_mov_b32_e32 v67, v64
	v_mov_b32_e32 v68, v64
	v_mov_b32_e32 v69, v64
	v_mov_b32_e32 v70, v64
	v_mov_b32_e32 v71, v64
	v_mov_b32_e32 v72, v64
	v_mov_b32_e32 v73, v64
	v_mov_b32_e32 v74, v64
	v_mov_b32_e32 v75, v64
	v_mov_b32_e32 v76, v64
	v_mov_b32_e32 v77, v64
	v_mov_b32_e32 v78, v64
	v_mov_b32_e32 v79, v64
	v_mov_b32_e32 v96, 0xff800000
	v_mov_b32_e32 v97, 0xff800000
	v_mov_b32_e32 v98, 0xff800000
	v_mov_b32_e32 v99, 0xff800000
	v_mov_b32_e32 v100, 0xff800000
	v_mov_b32_e32 v101, 0xff800000
	v_mov_b32_e32 v102, 0xff800000
	v_mov_b32_e32 v103, 0xff800000
	v_mov_b32_e32 v104, 0xff800000
	v_mov_b32_e32 v105, 0xff800000
	v_mov_b32_e32 v106, 0xff800000
	v_mov_b32_e32 v107, 0xff800000
	v_mov_b32_e32 v108, 0xff800000
	v_mov_b32_e32 v109, 0xff800000
	v_mov_b32_e32 v110, 0xff800000
	v_mov_b32_e32 v111, 0xff800000
	v_mov_b32_e32 v80, 0xff800000
	v_mov_b32_e32 v81, 0xff800000
	v_mov_b32_e32 v82, 0xff800000
	v_mov_b32_e32 v83, 0xff800000
	v_mov_b32_e32 v84, 0xff800000
	v_mov_b32_e32 v85, 0xff800000
	v_mov_b32_e32 v86, 0xff800000
	v_mov_b32_e32 v87, 0xff800000
	v_mov_b32_e32 v88, 0xff800000
	v_mov_b32_e32 v89, 0xff800000
	v_mov_b32_e32 v90, 0xff800000
	v_mov_b32_e32 v91, 0xff800000
	v_mov_b32_e32 v92, 0xff800000
	v_mov_b32_e32 v93, 0xff800000
	v_mov_b32_e32 v94, 0xff800000
	v_mov_b32_e32 v95, 0xff800000
	s_mov_b32 s10, 1
	s_mov_b32 s3, 0
	s_waitcnt vmcnt(0)
	ds_write_b128 v216, v[240:243] offset:45056
	s_and_saveexec_b64 vcc, s[4:5]
	ds_write_b128 v217, v[244:247] offset:45056
	s_mov_b64 exec, vcc
	ds_write2_b64 v238, v[248:249], v[250:251] offset0:128 offset1:130
	s_nop 3
	s_mov_b32 s2, 0x9000
	s_movk_i32 s0, 0x180
	v_lshl_add_u64 v[184:185], v[194:195], 0, s[2:3]
	v_lshl_add_u64 v[180:181], v[196:197], 0, s[2:3]
	v_lshl_add_u64 v[176:177], v[198:199], 0, s[0:1]
	global_load_dwordx4 v[184:187], v[184:185], off
	global_load_dwordx4 v[180:183], v[180:181], off
	global_load_dwordx4 v[176:179], v[176:177], off
	s_waitcnt lgkmcnt(0)
	s_barrier
	ds_read_b128 v[222:225], v220
	ds_read_b128 v[226:229], v220 offset:6656
	ds_read_b128 v[230:233], v220 offset:32
	ds_read_b128 v[234:237], v220 offset:6688
